# v87 + the four K-loop heads (back-edge targets only) aligned to 256 bytes
# baseline (speedup 1.0000x reference)
; #define PG8_STAGE(bufoff, gbase, voff) do { _Pragma("unroll") for (int _i = 0; _i < 2; ++_i) \
;         __builtin_amdgcn_global_load_lds((const unsigned*)((const char*)(gbase) + (voff)[_i]), (PG8_LAS unsigned*)(lds + (bufoff) + ldsw + _i * 8192), 16, 0, 0); } while (0)
; #define PG8_LDA(dst, b, h) do { _Pragma("unroll") for (int m = 0; m < 4; ++m) _Pragma("unroll") for (int k = 0; k < 2; ++k) dst[m][k] = *(const PG8_LAS bf16x8*)(lds + PG8_SA(b, h) + aoff + m * 2048 + k * 1024); } while (0)
; #define PG8_LDB(dst, b, h) do { _Pragma("unroll") for (int n = 0; n < 2; ++n) _Pragma("unroll") for (int k = 0; k < 2; ++k) dst[n][k] = *(const PG8_LAS bf16x8*)(lds + PG8_SB(b, h) + boff + n * 2048 + k * 1024); } while (0)
; #define PG8_MMA(ai, bj, At, Bt) do { __builtin_amdgcn_s_setprio(1); _Pragma("unroll") for (int m = 0; m < 4; ++m) _Pragma("unroll") for (int n = 0; n < 2; ++n) _Pragma("unroll") for (int k = 0; k < 2; ++k) \
;         acc[ai][bj][m][n] = __builtin_amdgcn_mfma_f32_16x16x32_bf16(Bt[n][k], At[m][k], acc[ai][bj][m][n], 0, 0, 0); __builtin_amdgcn_s_setprio(0); } while (0)
; #define PG8_WAIT_V(n) asm volatile("s_waitcnt vmcnt(" #n ")" ::: "memory")
; #define PG8_WAIT_L(n) asm volatile("s_waitcnt lgkmcnt(" #n ")" ::: "memory")
; #define PG8_BAR __builtin_amdgcn_s_barrier()
; template <class Epi, class Sched, bool ALIGN_EPI = false, bool SP2 = false>
; __device__ __forceinline__ void gemm_phase(PG8_LAS unsigned char* lds, const Gemm g, const Sched& S, const Epi& E) {
;     ...
;         const bool has_next = S.next(ui + 1, nxt);
;         const char* nA = has_next ? (const char*)g.A + (size_t)nxt.pm * tstep : cA; const char* nB = has_next ? (const char*)g.Bt + (size_t)nxt.pn * tstep : cB;
;         for (int t = 0; t < nt; t += 2) {
;             const bool last = (t == nt - 2);
;             const char* a1 = cA + (size_t)(t + 1) * kstep;
;             const char* a2 = last ? nA : cA + (size_t)(t + 2) * kstep; const char* b2 = last ? nB : cB + (size_t)(t + 2) * kstep;
;             const char* a3 = a2 + kstep; const char* b3 = b2 + kstep;
;             if (last && has_next) S.a_ready(nxt);
;             if constexpr (SP2) {
;             PG8_LDB(B0, 0, 0); PG8_LDB(B1, 0, 1); PG8_SCHED; PG8_LDA(At, 0, 0); PG8_STAGE(PG8_SA(1, 1), a1 + hstep, voffA);
;             PG8_WAIT_V(8); PG8_WAIT_L(0); PG8_BAR; PG8_MMA(0, 0, At, B0); PG8_MMA(0, 1, At, B1); PG8_BAR; PG8_SCHED;
.LBB0_99:
	s_ashr_i32 s21, s20, 31
	s_lshl_b64 s[24:25], s[20:21], 19
	s_add_u32 s24, s35, s24
	s_addc_u32 s25, s38, s25
	s_and_b64 s[26:27], s[4:5], exec
	s_cselect_b32 s3, s25, s9
	s_cselect_b32 s7, s24, s8
	s_ashr_i32 s23, s22, 31
	s_lshl_b64 s[26:27], s[22:23], 19
	s_add_u32 s26, s39, s26
	s_addc_u32 s27, s40, s27
	s_and_b64 s[30:31], s[4:5], exec
	s_cselect_b32 s11, s27, s29
	s_cselect_b32 s21, s26, s28
	s_add_u32 s8, s8, 0x40080
	s_addc_u32 s9, s9, 0
	s_add_u32 s23, s28, 0x100
	s_addc_u32 s44, s29, 0
	s_mov_b32 s45, -2
	s_add_u32 s28, s8, 0xfffc0080
	s_addc_u32 s29, s9, -1
	s_cmp_eq_u32 s45, 12
	s_cselect_b32 s31, s3, s29
	s_cselect_b32 s30, s7, s28
	s_cselect_b32 s29, s11, s44
	s_cselect_b32 s28, s21, s23
	ds_read_b128 v[132:135], v204
	ds_read_b128 v[136:139], v204 offset:1024
	ds_read_b128 v[140:143], v204 offset:2048
	ds_read_b128 v[144:147], v204 offset:3072
	ds_read_b128 v[148:151], v204 offset:16384
	ds_read_b128 v[152:155], v204 offset:17408
	ds_read_b128 v[156:159], v204 offset:18432
	ds_read_b128 v[160:163], v204 offset:19456
	v_lshl_add_u64 v[194:195], s[8:9], 0, v[178:179]
	s_add_i32 m0, s42, 0xc000
	ds_read_b128 v[164:167], v205
	ds_read_b128 v[182:185], v205 offset:1024
	ds_read_b128 v[186:189], v205 offset:2048
	ds_read_b128 v[190:193], v205 offset:3072
	ds_read_b128 v[208:211], v205 offset:4096
	ds_read_b128 v[212:215], v205 offset:5120
	ds_read_b128 v[216:219], v205 offset:6144
	ds_read_b128 v[220:223], v205 offset:7168
	global_load_lds_dwordx4 v[194:195], off
	s_add_i32 m0, s42, 0xe000
	v_lshl_add_u64 v[194:195], s[8:9], 0, v[180:181]
	global_load_lds_dwordx4 v[194:195], off
	s_waitcnt vmcnt(8) lgkmcnt(0)
	s_barrier
	s_setprio 1
	v_mfma_f32_16x16x32_bf16 v[128:131], v[132:135], v[164:167], 0
	v_mfma_f32_16x16x32_bf16 v[124:127], v[140:143], v[164:167], 0
	v_mfma_f32_16x16x32_bf16 v[112:115], v[132:135], v[186:189], 0
	v_mfma_f32_16x16x32_bf16 v[108:111], v[140:143], v[186:189], 0
	v_mfma_f32_16x16x32_bf16 v[96:99], v[132:135], v[208:211], 0
	v_mfma_f32_16x16x32_bf16 v[92:95], v[140:143], v[208:211], 0
	v_mfma_f32_16x16x32_bf16 v[80:83], v[132:135], v[216:219], 0
	v_mfma_f32_16x16x32_bf16 v[76:79], v[140:143], v[216:219], 0
	v_mfma_f32_16x16x32_bf16 v[128:131], v[136:139], v[182:185], v[128:131]
	v_mfma_f32_16x16x32_bf16 v[124:127], v[144:147], v[182:185], v[124:127]
	v_mfma_f32_16x16x32_bf16 v[112:115], v[136:139], v[190:193], v[112:115]
	v_mfma_f32_16x16x32_bf16 v[108:111], v[144:147], v[190:193], v[108:111]
	v_mfma_f32_16x16x32_bf16 v[96:99], v[136:139], v[212:215], v[96:99]
	v_mfma_f32_16x16x32_bf16 v[92:95], v[144:147], v[212:215], v[92:95]
	v_mfma_f32_16x16x32_bf16 v[80:83], v[136:139], v[220:223], v[80:83]
	v_mfma_f32_16x16x32_bf16 v[76:79], v[144:147], v[220:223], v[76:79]
	s_setprio 0
	s_setprio 1
	v_mfma_f32_16x16x32_bf16 v[120:123], v[148:151], v[164:167], 0
	v_mfma_f32_16x16x32_bf16 v[116:119], v[156:159], v[164:167], 0
	v_mfma_f32_16x16x32_bf16 v[104:107], v[148:151], v[186:189], 0
	v_mfma_f32_16x16x32_bf16 v[100:103], v[156:159], v[186:189], 0
	v_mfma_f32_16x16x32_bf16 v[88:91], v[148:151], v[208:211], 0
	v_mfma_f32_16x16x32_bf16 v[84:87], v[156:159], v[208:211], 0
	v_mfma_f32_16x16x32_bf16 v[72:75], v[148:151], v[216:219], 0
	v_mfma_f32_16x16x32_bf16 v[68:71], v[156:159], v[216:219], 0
	v_mfma_f32_16x16x32_bf16 v[120:123], v[152:155], v[182:185], v[120:123]
	v_mfma_f32_16x16x32_bf16 v[116:119], v[160:163], v[182:185], v[116:119]
	v_mfma_f32_16x16x32_bf16 v[104:107], v[152:155], v[190:193], v[104:107]
	v_mfma_f32_16x16x32_bf16 v[100:103], v[160:163], v[190:193], v[100:103]
	v_mfma_f32_16x16x32_bf16 v[88:91], v[152:155], v[212:215], v[88:91]
	v_mfma_f32_16x16x32_bf16 v[84:87], v[160:163], v[212:215], v[84:87]
	v_mfma_f32_16x16x32_bf16 v[72:75], v[152:155], v[220:223], v[72:75]
	v_mfma_f32_16x16x32_bf16 v[68:71], v[160:163], v[220:223], v[68:71]
	s_setprio 0
	s_barrier
; #define PG8_STAGE(bufoff, gbase, voff) do { _Pragma("unroll") for (int _i = 0; _i < 2; ++_i) \
;         __builtin_amdgcn_global_load_lds((const unsigned*)((const char*)(gbase) + (voff)[_i]), (PG8_LAS unsigned*)(lds + (bufoff) + ldsw + _i * 8192), 16, 0, 0); } while (0)
; #define PG8_LDA(dst, b, h) do { _Pragma("unroll") for (int m = 0; m < 4; ++m) _Pragma("unroll") for (int k = 0; k < 2; ++k) dst[m][k] = *(const PG8_LAS bf16x8*)(lds + PG8_SA(b, h) + aoff + m * 2048 + k * 1024); } while (0)
; #define PG8_MMA(ai, bj, At, Bt) do { __builtin_amdgcn_s_setprio(1); _Pragma("unroll") for (int m = 0; m < 4; ++m) _Pragma("unroll") for (int n = 0; n < 2; ++n) _Pragma("unroll") for (int k = 0; k < 2; ++k) \
;         acc[ai][bj][m][n] = __builtin_amdgcn_mfma_f32_16x16x32_bf16(Bt[n][k], At[m][k], acc[ai][bj][m][n], 0, 0, 0); __builtin_amdgcn_s_setprio(0); } while (0)
; #define PG8_WAIT_V(n) asm volatile("s_waitcnt vmcnt(" #n ")" ::: "memory")
; #define PG8_WAIT_L(n) asm volatile("s_waitcnt lgkmcnt(" #n ")" ::: "memory")
; #define PG8_BAR __builtin_amdgcn_s_barrier()
; #define PG8_SCHED __builtin_amdgcn_sched_barrier(0)
; template <class Epi, class Sched, bool ALIGN_EPI = false, bool SP2 = false>
; __device__ __forceinline__ void gemm_phase(PG8_LAS unsigned char* lds, const Gemm g, const Sched& S, const Epi& E) {
;     ...
;             PG8_LDA(At, 0, 1); PG8_STAGE(PG8_SB(0, 0), b2, voffB); PG8_STAGE(PG8_SB(0, 1), b2 + hstep, voffB); PG8_STAGE(PG8_SA(0, 0), a2, voffA);
;             PG8_WAIT_V(8); PG8_WAIT_L(0); PG8_BAR; PG8_MMA(1, 0, At, B0); PG8_MMA(1, 1, At, B1); PG8_BAR; PG8_SCHED;
	v_lshl_add_u64 v[194:195], s[28:29], 0, v[168:169]
	s_add_i32 m0, s41, 0x10000
	ds_read_b128 v[164:167], v205 offset:16384
	ds_read_b128 v[182:185], v205 offset:17408
	ds_read_b128 v[186:189], v205 offset:18432
	ds_read_b128 v[190:193], v205 offset:19456
	ds_read_b128 v[208:211], v205 offset:20480
	ds_read_b128 v[212:215], v205 offset:21504
	ds_read_b128 v[216:219], v205 offset:22528
	ds_read_b128 v[220:223], v205 offset:23552
	global_load_lds_dwordx4 v[194:195], off
	s_add_i32 m0, s41, 0x12000
	s_add_u32 s54, s28, 0x40000
	v_lshl_add_u64 v[202:203], s[28:29], 0, v[172:173]
	s_addc_u32 s55, s29, 0
	global_load_lds_dwordx4 v[202:203], off
	v_lshl_add_u64 v[224:225], s[54:55], 0, v[168:169]
	s_add_i32 m0, s41, 0x14000
	v_lshl_add_u64 v[226:227], s[30:31], 0, v[170:171]
	global_load_lds_dwordx4 v[224:225], off
	s_add_i32 m0, s41, 0x16000
	v_lshl_add_u64 v[224:225], s[54:55], 0, v[172:173]
	global_load_lds_dwordx4 v[224:225], off
	s_mov_b32 m0, s42
	v_lshl_add_u64 v[224:225], s[30:31], 0, v[0:1]
	global_load_lds_dwordx4 v[224:225], off
	s_mov_b32 m0, s43
	s_add_i32 s53, 0, 0x18000
	global_load_lds_dwordx4 v[226:227], off
	s_waitcnt vmcnt(8) lgkmcnt(0)
	s_barrier
	s_setprio 1
	v_mfma_f32_16x16x32_bf16 v[64:67], v[132:135], v[164:167], 0
	v_mfma_f32_16x16x32_bf16 v[60:63], v[140:143], v[164:167], 0
	v_mfma_f32_16x16x32_bf16 v[48:51], v[132:135], v[186:189], 0
	v_mfma_f32_16x16x32_bf16 v[44:47], v[140:143], v[186:189], 0
	v_mfma_f32_16x16x32_bf16 v[32:35], v[132:135], v[208:211], 0
	v_mfma_f32_16x16x32_bf16 v[28:31], v[140:143], v[208:211], 0
	v_mfma_f32_16x16x32_bf16 v[16:19], v[132:135], v[216:219], 0
	v_mfma_f32_16x16x32_bf16 v[12:15], v[140:143], v[216:219], 0
	v_mfma_f32_16x16x32_bf16 v[64:67], v[136:139], v[182:185], v[64:67]
	v_mfma_f32_16x16x32_bf16 v[60:63], v[144:147], v[182:185], v[60:63]
	v_mfma_f32_16x16x32_bf16 v[48:51], v[136:139], v[190:193], v[48:51]
	v_mfma_f32_16x16x32_bf16 v[44:47], v[144:147], v[190:193], v[44:47]
	v_mfma_f32_16x16x32_bf16 v[32:35], v[136:139], v[212:215], v[32:35]
	v_mfma_f32_16x16x32_bf16 v[28:31], v[144:147], v[212:215], v[28:31]
	v_mfma_f32_16x16x32_bf16 v[16:19], v[136:139], v[220:223], v[16:19]
	v_mfma_f32_16x16x32_bf16 v[12:15], v[144:147], v[220:223], v[12:15]
	s_setprio 0
	s_setprio 1
	v_mfma_f32_16x16x32_bf16 v[56:59], v[148:151], v[164:167], 0
	v_mfma_f32_16x16x32_bf16 v[52:55], v[156:159], v[164:167], 0
	v_mfma_f32_16x16x32_bf16 v[40:43], v[148:151], v[186:189], 0
	v_mfma_f32_16x16x32_bf16 v[36:39], v[156:159], v[186:189], 0
	v_mfma_f32_16x16x32_bf16 v[24:27], v[148:151], v[208:211], 0
	v_mfma_f32_16x16x32_bf16 v[20:23], v[156:159], v[208:211], 0
	v_mfma_f32_16x16x32_bf16 v[8:11], v[148:151], v[216:219], 0
	v_mfma_f32_16x16x32_bf16 v[4:7], v[156:159], v[216:219], 0
	v_mfma_f32_16x16x32_bf16 v[56:59], v[152:155], v[182:185], v[56:59]
	v_mfma_f32_16x16x32_bf16 v[52:55], v[160:163], v[182:185], v[52:55]
	v_mfma_f32_16x16x32_bf16 v[40:43], v[152:155], v[190:193], v[40:43]
	v_mfma_f32_16x16x32_bf16 v[36:39], v[160:163], v[190:193], v[36:39]
	v_mfma_f32_16x16x32_bf16 v[24:27], v[152:155], v[212:215], v[24:27]
	v_mfma_f32_16x16x32_bf16 v[20:23], v[160:163], v[212:215], v[20:23]
	v_mfma_f32_16x16x32_bf16 v[8:11], v[152:155], v[220:223], v[8:11]
	v_mfma_f32_16x16x32_bf16 v[4:7], v[160:163], v[220:223], v[4:7]
	s_setprio 0
	s_barrier
	s_branch .Lkmid_0
	.p2align	8

; #define PG8_STAGE(bufoff, gbase, voff) do { _Pragma("unroll") for (int _i = 0; _i < 2; ++_i) \
;         __builtin_amdgcn_global_load_lds((const unsigned*)((const char*)(gbase) + (voff)[_i]), (PG8_LAS unsigned*)(lds + (bufoff) + ldsw + _i * 8192), 16, 0, 0); } while (0)
; #define PG8_LDA(dst, b, h) do { _Pragma("unroll") for (int m = 0; m < 4; ++m) _Pragma("unroll") for (int k = 0; k < 2; ++k) dst[m][k] = *(const PG8_LAS bf16x8*)(lds + PG8_SA(b, h) + aoff + m * 2048 + k * 1024); } while (0)
; #define PG8_LDB(dst, b, h) do { _Pragma("unroll") for (int n = 0; n < 2; ++n) _Pragma("unroll") for (int k = 0; k < 2; ++k) dst[n][k] = *(const PG8_LAS bf16x8*)(lds + PG8_SB(b, h) + boff + n * 2048 + k * 1024); } while (0)
; #define PG8_MMA(ai, bj, At, Bt) do { __builtin_amdgcn_s_setprio(1); _Pragma("unroll") for (int m = 0; m < 4; ++m) _Pragma("unroll") for (int n = 0; n < 2; ++n) _Pragma("unroll") for (int k = 0; k < 2; ++k) \
;         acc[ai][bj][m][n] = __builtin_amdgcn_mfma_f32_16x16x32_bf16(Bt[n][k], At[m][k], acc[ai][bj][m][n], 0, 0, 0); __builtin_amdgcn_s_setprio(0); } while (0)
; #define PG8_WAIT_V(n) asm volatile("s_waitcnt vmcnt(" #n ")" ::: "memory")
; #define PG8_WAIT_L(n) asm volatile("s_waitcnt lgkmcnt(" #n ")" ::: "memory")
; #define PG8_BAR __builtin_amdgcn_s_barrier()
; template <class Epi, class Sched, bool ALIGN_EPI = false, bool SP2 = false>
; __device__ __forceinline__ void gemm_phase(PG8_LAS unsigned char* lds, const Gemm g, const Sched& S, const Epi& E) {
;     ...
;         const bool has_next = S.next(ui + 1, nxt);
;         const char* nA = has_next ? (const char*)g.A + (size_t)nxt.pm * tstep : cA; const char* nB = has_next ? (const char*)g.Bt + (size_t)nxt.pn * tstep : cB;
;         for (int t = 0; t < nt; t += 2) {
;             const bool last = (t == nt - 2);
;             const char* a1 = cA + (size_t)(t + 1) * kstep;
;             const char* a2 = last ? nA : cA + (size_t)(t + 2) * kstep; const char* b2 = last ? nB : cB + (size_t)(t + 2) * kstep;
;             const char* a3 = a2 + kstep; const char* b3 = b2 + kstep;
;             if (last && has_next) S.a_ready(nxt);
;             if constexpr (SP2) {
;             PG8_LDB(B0, 0, 0); PG8_LDB(B1, 0, 1); PG8_SCHED; PG8_LDA(At, 0, 0); PG8_STAGE(PG8_SA(1, 1), a1 + hstep, voffA);
;             PG8_WAIT_V(8); PG8_WAIT_L(0); PG8_BAR; PG8_MMA(0, 0, At, B0); PG8_MMA(0, 1, At, B1); PG8_BAR; PG8_SCHED;
.LBB0_328:
	s_ashr_i32 s17, s16, 31
	s_lshl_b64 s[20:21], s[16:17], 19
	s_add_u32 s20, s37, s20
	s_addc_u32 s21, s38, s21
	s_and_b64 s[22:23], s[6:7], exec
	s_cselect_b32 s3, s21, s29
	s_cselect_b32 s17, s20, s28
	s_ashr_i32 s19, s18, 31
	s_lshl_b64 s[22:23], s[18:19], 19
	s_add_u32 s22, s39, s22
	s_addc_u32 s23, s40, s23
	s_and_b64 s[34:35], s[6:7], exec
	s_cselect_b32 s19, s23, s31
	s_cselect_b32 s25, s22, s30
	s_add_u32 s28, s28, 0x40080
	s_addc_u32 s29, s29, 0
	s_add_u32 s27, s30, 0x100
	s_addc_u32 s44, s31, 0
	s_mov_b32 s45, -2
	s_add_u32 s30, s28, 0xfffc0080
	s_addc_u32 s31, s29, -1
	s_cmp_eq_u32 s45, 12
	s_cselect_b32 s35, s3, s31
	s_cselect_b32 s34, s17, s30
	s_cselect_b32 s31, s19, s44
	s_cselect_b32 s30, s25, s27
	ds_read_b128 v[108:111], v251
	ds_read_b128 v[112:115], v251 offset:1024
	ds_read_b128 v[124:127], v251 offset:2048
	ds_read_b128 v[128:131], v251 offset:3072
	ds_read_b128 v[132:135], v251 offset:16384
	ds_read_b128 v[140:143], v251 offset:17408
	ds_read_b128 v[148:151], v251 offset:18432
	ds_read_b128 v[156:159], v251 offset:19456
	v_lshl_add_u64 v[212:213], s[28:29], 0, v[208:209]
	s_add_i32 m0, s42, 0xc000
	ds_read_b128 v[164:167], v253
	ds_read_b128 v[168:171], v253 offset:1024
	ds_read_b128 v[172:175], v253 offset:2048
	ds_read_b128 v[176:179], v253 offset:3072
	ds_read_b128 v[180:183], v253 offset:4096
	ds_read_b128 v[184:187], v253 offset:5120
	ds_read_b128 v[188:191], v253 offset:6144
	ds_read_b128 v[192:195], v253 offset:7168
	global_load_lds_dwordx4 v[212:213], off
	s_add_i32 m0, s42, 0xe000
	v_lshl_add_u64 v[212:213], s[28:29], 0, v[210:211]
	global_load_lds_dwordx4 v[212:213], off
	s_waitcnt vmcnt(8) lgkmcnt(0)
	s_barrier
	s_setprio 1
	v_mfma_f32_16x16x32_bf16 v[160:163], v[108:111], v[164:167], 0
	v_mfma_f32_16x16x32_bf16 v[152:155], v[124:127], v[164:167], 0
	v_mfma_f32_16x16x32_bf16 v[120:123], v[108:111], v[172:175], 0
	v_mfma_f32_16x16x32_bf16 v[116:119], v[124:127], v[172:175], 0
	v_mfma_f32_16x16x32_bf16 v[96:99], v[108:111], v[180:183], 0
	v_mfma_f32_16x16x32_bf16 v[92:95], v[124:127], v[180:183], 0
	v_mfma_f32_16x16x32_bf16 v[80:83], v[108:111], v[188:191], 0
	v_mfma_f32_16x16x32_bf16 v[76:79], v[124:127], v[188:191], 0
	v_mfma_f32_16x16x32_bf16 v[160:163], v[112:115], v[168:171], v[160:163]
	v_mfma_f32_16x16x32_bf16 v[152:155], v[128:131], v[168:171], v[152:155]
	v_mfma_f32_16x16x32_bf16 v[120:123], v[112:115], v[176:179], v[120:123]
	v_mfma_f32_16x16x32_bf16 v[116:119], v[128:131], v[176:179], v[116:119]
	v_mfma_f32_16x16x32_bf16 v[96:99], v[112:115], v[184:187], v[96:99]
	v_mfma_f32_16x16x32_bf16 v[92:95], v[128:131], v[184:187], v[92:95]
	v_mfma_f32_16x16x32_bf16 v[80:83], v[112:115], v[192:195], v[80:83]
	v_mfma_f32_16x16x32_bf16 v[76:79], v[128:131], v[192:195], v[76:79]
	s_setprio 0
	s_setprio 1
	v_mfma_f32_16x16x32_bf16 v[144:147], v[132:135], v[164:167], 0
	v_mfma_f32_16x16x32_bf16 v[136:139], v[148:151], v[164:167], 0
	v_mfma_f32_16x16x32_bf16 v[104:107], v[132:135], v[172:175], 0
	v_mfma_f32_16x16x32_bf16 v[100:103], v[148:151], v[172:175], 0
	v_mfma_f32_16x16x32_bf16 v[88:91], v[132:135], v[180:183], 0
	v_mfma_f32_16x16x32_bf16 v[84:87], v[148:151], v[180:183], 0
	v_mfma_f32_16x16x32_bf16 v[72:75], v[132:135], v[188:191], 0
	v_mfma_f32_16x16x32_bf16 v[68:71], v[148:151], v[188:191], 0
	v_mfma_f32_16x16x32_bf16 v[144:147], v[140:143], v[168:171], v[144:147]
	v_mfma_f32_16x16x32_bf16 v[136:139], v[156:159], v[168:171], v[136:139]
	v_mfma_f32_16x16x32_bf16 v[104:107], v[140:143], v[176:179], v[104:107]
	v_mfma_f32_16x16x32_bf16 v[100:103], v[156:159], v[176:179], v[100:103]
	v_mfma_f32_16x16x32_bf16 v[88:91], v[140:143], v[184:187], v[88:91]
	v_mfma_f32_16x16x32_bf16 v[84:87], v[156:159], v[184:187], v[84:87]
	v_mfma_f32_16x16x32_bf16 v[72:75], v[140:143], v[192:195], v[72:75]
	v_mfma_f32_16x16x32_bf16 v[68:71], v[156:159], v[192:195], v[68:71]
	s_setprio 0
	s_barrier
; #define PG8_STAGE(bufoff, gbase, voff) do { _Pragma("unroll") for (int _i = 0; _i < 2; ++_i) \
;         __builtin_amdgcn_global_load_lds((const unsigned*)((const char*)(gbase) + (voff)[_i]), (PG8_LAS unsigned*)(lds + (bufoff) + ldsw + _i * 8192), 16, 0, 0); } while (0)
; #define PG8_LDA(dst, b, h) do { _Pragma("unroll") for (int m = 0; m < 4; ++m) _Pragma("unroll") for (int k = 0; k < 2; ++k) dst[m][k] = *(const PG8_LAS bf16x8*)(lds + PG8_SA(b, h) + aoff + m * 2048 + k * 1024); } while (0)
; #define PG8_MMA(ai, bj, At, Bt) do { __builtin_amdgcn_s_setprio(1); _Pragma("unroll") for (int m = 0; m < 4; ++m) _Pragma("unroll") for (int n = 0; n < 2; ++n) _Pragma("unroll") for (int k = 0; k < 2; ++k) \
;         acc[ai][bj][m][n] = __builtin_amdgcn_mfma_f32_16x16x32_bf16(Bt[n][k], At[m][k], acc[ai][bj][m][n], 0, 0, 0); __builtin_amdgcn_s_setprio(0); } while (0)
; #define PG8_WAIT_V(n) asm volatile("s_waitcnt vmcnt(" #n ")" ::: "memory")
; #define PG8_WAIT_L(n) asm volatile("s_waitcnt lgkmcnt(" #n ")" ::: "memory")
; #define PG8_BAR __builtin_amdgcn_s_barrier()
; #define PG8_SCHED __builtin_amdgcn_sched_barrier(0)
; template <class Epi, class Sched, bool ALIGN_EPI = false, bool SP2 = false>
; __device__ __forceinline__ void gemm_phase(PG8_LAS unsigned char* lds, const Gemm g, const Sched& S, const Epi& E) {
;     ...
;             PG8_LDA(At, 0, 1); PG8_STAGE(PG8_SB(0, 0), b2, voffB); PG8_STAGE(PG8_SB(0, 1), b2 + hstep, voffB); PG8_STAGE(PG8_SA(0, 0), a2, voffA);
;             PG8_WAIT_V(8); PG8_WAIT_L(0); PG8_BAR; PG8_MMA(1, 0, At, B0); PG8_MMA(1, 1, At, B1); PG8_BAR; PG8_SCHED;
	v_lshl_add_u64 v[212:213], s[30:31], 0, v[202:203]
	s_add_i32 m0, s41, 0x10000
	ds_read_b128 v[164:167], v253 offset:16384
	ds_read_b128 v[168:171], v253 offset:17408
	ds_read_b128 v[172:175], v253 offset:18432
	ds_read_b128 v[176:179], v253 offset:19456
	ds_read_b128 v[180:183], v253 offset:20480
	ds_read_b128 v[184:187], v253 offset:21504
	ds_read_b128 v[188:191], v253 offset:22528
	ds_read_b128 v[192:195], v253 offset:23552
	global_load_lds_dwordx4 v[212:213], off
	s_add_i32 m0, s41, 0x12000
	s_add_u32 s52, s30, 0x40000
	v_lshl_add_u64 v[214:215], s[30:31], 0, v[206:207]
	s_addc_u32 s53, s31, 0
	global_load_lds_dwordx4 v[214:215], off
	v_lshl_add_u64 v[216:217], s[52:53], 0, v[202:203]
	s_add_i32 m0, s41, 0x14000
	v_lshl_add_u64 v[218:219], s[34:35], 0, v[204:205]
	global_load_lds_dwordx4 v[216:217], off
	s_add_i32 m0, s41, 0x16000
	v_lshl_add_u64 v[216:217], s[52:53], 0, v[206:207]
	global_load_lds_dwordx4 v[216:217], off
	s_mov_b32 m0, s42
	v_lshl_add_u64 v[216:217], s[34:35], 0, v[0:1]
	global_load_lds_dwordx4 v[216:217], off
	s_mov_b32 m0, s43
	s_add_i32 s52, 0, 0x18000
	global_load_lds_dwordx4 v[218:219], off
	s_waitcnt vmcnt(8) lgkmcnt(0)
	s_barrier
	s_setprio 1
	v_mfma_f32_16x16x32_bf16 v[64:67], v[108:111], v[164:167], 0
	v_mfma_f32_16x16x32_bf16 v[60:63], v[124:127], v[164:167], 0
	v_mfma_f32_16x16x32_bf16 v[48:51], v[108:111], v[172:175], 0
	v_mfma_f32_16x16x32_bf16 v[44:47], v[124:127], v[172:175], 0
	v_mfma_f32_16x16x32_bf16 v[32:35], v[108:111], v[180:183], 0
	v_mfma_f32_16x16x32_bf16 v[28:31], v[124:127], v[180:183], 0
	v_mfma_f32_16x16x32_bf16 v[16:19], v[108:111], v[188:191], 0
	v_mfma_f32_16x16x32_bf16 v[12:15], v[124:127], v[188:191], 0
	v_mfma_f32_16x16x32_bf16 v[64:67], v[112:115], v[168:171], v[64:67]
	v_mfma_f32_16x16x32_bf16 v[60:63], v[128:131], v[168:171], v[60:63]
	v_mfma_f32_16x16x32_bf16 v[48:51], v[112:115], v[176:179], v[48:51]
	v_mfma_f32_16x16x32_bf16 v[44:47], v[128:131], v[176:179], v[44:47]
	v_mfma_f32_16x16x32_bf16 v[32:35], v[112:115], v[184:187], v[32:35]
	v_mfma_f32_16x16x32_bf16 v[28:31], v[128:131], v[184:187], v[28:31]
	v_mfma_f32_16x16x32_bf16 v[16:19], v[112:115], v[192:195], v[16:19]
	v_mfma_f32_16x16x32_bf16 v[12:15], v[128:131], v[192:195], v[12:15]
	s_setprio 0
	s_setprio 1
	v_mfma_f32_16x16x32_bf16 v[56:59], v[132:135], v[164:167], 0
	v_mfma_f32_16x16x32_bf16 v[52:55], v[148:151], v[164:167], 0
	v_mfma_f32_16x16x32_bf16 v[40:43], v[132:135], v[172:175], 0
	v_mfma_f32_16x16x32_bf16 v[36:39], v[148:151], v[172:175], 0
	v_mfma_f32_16x16x32_bf16 v[24:27], v[132:135], v[180:183], 0
	v_mfma_f32_16x16x32_bf16 v[20:23], v[148:151], v[180:183], 0
	v_mfma_f32_16x16x32_bf16 v[8:11], v[132:135], v[188:191], 0
	v_mfma_f32_16x16x32_bf16 v[4:7], v[148:151], v[188:191], 0
	v_mfma_f32_16x16x32_bf16 v[56:59], v[140:143], v[168:171], v[56:59]
	v_mfma_f32_16x16x32_bf16 v[52:55], v[156:159], v[168:171], v[52:55]
	v_mfma_f32_16x16x32_bf16 v[40:43], v[140:143], v[176:179], v[40:43]
	v_mfma_f32_16x16x32_bf16 v[36:39], v[156:159], v[176:179], v[36:39]
	v_mfma_f32_16x16x32_bf16 v[24:27], v[140:143], v[184:187], v[24:27]
	v_mfma_f32_16x16x32_bf16 v[20:23], v[156:159], v[184:187], v[20:23]
	v_mfma_f32_16x16x32_bf16 v[8:11], v[140:143], v[192:195], v[8:11]
	v_mfma_f32_16x16x32_bf16 v[4:7], v[156:159], v[192:195], v[4:7]
	s_setprio 0
	s_barrier
	s_branch .Lkmid_1
	.p2align	8

; #define PG8_STAGE(bufoff, gbase, voff) do { _Pragma("unroll") for (int _i = 0; _i < 2; ++_i) \
;         __builtin_amdgcn_global_load_lds((const unsigned*)((const char*)(gbase) + (voff)[_i]), (PG8_LAS unsigned*)(lds + (bufoff) + ldsw + _i * 8192), 16, 0, 0); } while (0)
; #define PG8_LDA(dst, b, h) do { _Pragma("unroll") for (int m = 0; m < 4; ++m) _Pragma("unroll") for (int k = 0; k < 2; ++k) dst[m][k] = *(const PG8_LAS bf16x8*)(lds + PG8_SA(b, h) + aoff + m * 2048 + k * 1024); } while (0)
; #define PG8_LDB(dst, b, h) do { _Pragma("unroll") for (int n = 0; n < 2; ++n) _Pragma("unroll") for (int k = 0; k < 2; ++k) dst[n][k] = *(const PG8_LAS bf16x8*)(lds + PG8_SB(b, h) + boff + n * 2048 + k * 1024); } while (0)
; #define PG8_MMA(ai, bj, At, Bt) do { __builtin_amdgcn_s_setprio(1); _Pragma("unroll") for (int m = 0; m < 4; ++m) _Pragma("unroll") for (int n = 0; n < 2; ++n) _Pragma("unroll") for (int k = 0; k < 2; ++k) \
;         acc[ai][bj][m][n] = __builtin_amdgcn_mfma_f32_16x16x32_bf16(Bt[n][k], At[m][k], acc[ai][bj][m][n], 0, 0, 0); __builtin_amdgcn_s_setprio(0); } while (0)
; #define PG8_WAIT_V(n) asm volatile("s_waitcnt vmcnt(" #n ")" ::: "memory")
; #define PG8_WAIT_L(n) asm volatile("s_waitcnt lgkmcnt(" #n ")" ::: "memory")
; #define PG8_BAR __builtin_amdgcn_s_barrier()
; template <class Epi, class Sched, bool ALIGN_EPI = false, bool SP2 = false>
; __device__ __forceinline__ void gemm_phase(PG8_LAS unsigned char* lds, const Gemm g, const Sched& S, const Epi& E) {
;     ...
;         const bool has_next = S.next(ui + 1, nxt);
;         const char* nA = has_next ? (const char*)g.A + (size_t)nxt.pm * tstep : cA; const char* nB = has_next ? (const char*)g.Bt + (size_t)nxt.pn * tstep : cB;
;         for (int t = 0; t < nt; t += 2) {
;             const bool last = (t == nt - 2);
;             const char* a1 = cA + (size_t)(t + 1) * kstep;
;             const char* a2 = last ? nA : cA + (size_t)(t + 2) * kstep; const char* b2 = last ? nB : cB + (size_t)(t + 2) * kstep;
;             const char* a3 = a2 + kstep; const char* b3 = b2 + kstep;
;             if (last && has_next) S.a_ready(nxt);
;             if constexpr (SP2) {
;             PG8_LDB(B0, 0, 0); PG8_LDB(B1, 0, 1); PG8_SCHED; PG8_LDA(At, 0, 0); PG8_STAGE(PG8_SA(1, 1), a1 + hstep, voffA);
;             PG8_WAIT_V(8); PG8_WAIT_L(0); PG8_BAR; PG8_MMA(0, 0, At, B0); PG8_MMA(0, 1, At, B1); PG8_BAR; PG8_SCHED;
.LBB0_404:
	s_ashr_i32 s17, s16, 31
	s_lshl_b64 s[20:21], s[16:17], 19
	s_add_u32 s20, s29, s20
	s_addc_u32 s21, s30, s21
	s_and_b64 s[22:23], s[4:5], exec
	s_cselect_b32 s7, s21, s9
	s_cselect_b32 s17, s20, s8
	s_ashr_i32 s19, s18, 31
	s_lshl_b64 s[22:23], s[18:19], 19
	s_add_u32 s22, s31, s22
	s_addc_u32 s23, s34, s23
	s_and_b64 s[26:27], s[4:5], exec
	s_cselect_b32 s19, s23, s25
	s_cselect_b32 s43, s22, s24
	s_add_u32 s8, s8, 0x40080
	s_addc_u32 s9, s9, 0
	s_add_u32 s44, s24, 0x100
	s_addc_u32 s45, s25, 0
	s_mov_b32 s46, -2
	s_add_u32 s24, s8, 0xfffc0080
	s_addc_u32 s25, s9, -1
	s_cmp_eq_u32 s46, 12
	s_cselect_b32 s27, s7, s25
	s_cselect_b32 s26, s17, s24
	s_cselect_b32 s25, s19, s45
	s_cselect_b32 s24, s43, s44
	s_add_i32 s50, 0, 0x14000
	ds_read_b128 v[144:147], v164
	ds_read_b128 v[148:151], v164 offset:1024
	ds_read_b128 v[152:155], v164 offset:2048
	ds_read_b128 v[156:159], v164 offset:3072
	ds_read_b128 v[160:163], v164 offset:16384
	ds_read_b128 v[168:171], v164 offset:17408
	ds_read_b128 v[172:175], v164 offset:18432
	ds_read_b128 v[176:179], v164 offset:19456
	v_lshl_add_u64 v[198:199], s[8:9], 0, v[140:141]
	s_add_i32 m0, s37, 0xc000
	ds_read_b128 v[180:183], v166
	ds_read_b128 v[184:187], v166 offset:1024
	ds_read_b128 v[188:191], v166 offset:2048
	ds_read_b128 v[192:195], v166 offset:3072
	ds_read_b128 v[202:205], v166 offset:4096
	ds_read_b128 v[206:209], v166 offset:5120
	ds_read_b128 v[210:213], v166 offset:6144
	ds_read_b128 v[214:217], v166 offset:7168
	global_load_lds_dwordx4 v[198:199], off
	s_add_i32 m0, s37, 0xe000
	v_lshl_add_u64 v[198:199], s[8:9], 0, v[142:143]
	global_load_lds_dwordx4 v[198:199], off
	s_waitcnt vmcnt(8) lgkmcnt(0)
	s_barrier
	s_setprio 1
	v_mfma_f32_16x16x32_bf16 v[128:131], v[144:147], v[180:183], 0
	v_mfma_f32_16x16x32_bf16 v[120:123], v[152:155], v[180:183], 0
	v_mfma_f32_16x16x32_bf16 v[112:115], v[144:147], v[188:191], 0
	v_mfma_f32_16x16x32_bf16 v[104:107], v[152:155], v[188:191], 0
	v_mfma_f32_16x16x32_bf16 v[96:99], v[144:147], v[202:205], 0
	v_mfma_f32_16x16x32_bf16 v[88:91], v[152:155], v[202:205], 0
	v_mfma_f32_16x16x32_bf16 v[80:83], v[144:147], v[210:213], 0
	v_mfma_f32_16x16x32_bf16 v[72:75], v[152:155], v[210:213], 0
	v_mfma_f32_16x16x32_bf16 v[128:131], v[148:151], v[184:187], v[128:131]
	v_mfma_f32_16x16x32_bf16 v[120:123], v[156:159], v[184:187], v[120:123]
	v_mfma_f32_16x16x32_bf16 v[112:115], v[148:151], v[192:195], v[112:115]
	v_mfma_f32_16x16x32_bf16 v[104:107], v[156:159], v[192:195], v[104:107]
	v_mfma_f32_16x16x32_bf16 v[96:99], v[148:151], v[206:209], v[96:99]
	v_mfma_f32_16x16x32_bf16 v[88:91], v[156:159], v[206:209], v[88:91]
	v_mfma_f32_16x16x32_bf16 v[80:83], v[148:151], v[214:217], v[80:83]
	v_mfma_f32_16x16x32_bf16 v[72:75], v[156:159], v[214:217], v[72:75]
	s_setprio 0
	s_setprio 1
	v_mfma_f32_16x16x32_bf16 v[124:127], v[160:163], v[180:183], 0
	v_mfma_f32_16x16x32_bf16 v[116:119], v[172:175], v[180:183], 0
	v_mfma_f32_16x16x32_bf16 v[108:111], v[160:163], v[188:191], 0
	v_mfma_f32_16x16x32_bf16 v[100:103], v[172:175], v[188:191], 0
	v_mfma_f32_16x16x32_bf16 v[92:95], v[160:163], v[202:205], 0
	v_mfma_f32_16x16x32_bf16 v[84:87], v[172:175], v[202:205], 0
	v_mfma_f32_16x16x32_bf16 v[76:79], v[160:163], v[210:213], 0
	v_mfma_f32_16x16x32_bf16 v[68:71], v[172:175], v[210:213], 0
	v_mfma_f32_16x16x32_bf16 v[124:127], v[168:171], v[184:187], v[124:127]
	v_mfma_f32_16x16x32_bf16 v[116:119], v[176:179], v[184:187], v[116:119]
	v_mfma_f32_16x16x32_bf16 v[108:111], v[168:171], v[192:195], v[108:111]
	v_mfma_f32_16x16x32_bf16 v[100:103], v[176:179], v[192:195], v[100:103]
	v_mfma_f32_16x16x32_bf16 v[92:95], v[168:171], v[206:209], v[92:95]
	v_mfma_f32_16x16x32_bf16 v[84:87], v[176:179], v[206:209], v[84:87]
	v_mfma_f32_16x16x32_bf16 v[76:79], v[168:171], v[214:217], v[76:79]
	v_mfma_f32_16x16x32_bf16 v[68:71], v[176:179], v[214:217], v[68:71]
	s_setprio 0
	s_barrier
; #define PG8_STAGE(bufoff, gbase, voff) do { _Pragma("unroll") for (int _i = 0; _i < 2; ++_i) \
;         __builtin_amdgcn_global_load_lds((const unsigned*)((const char*)(gbase) + (voff)[_i]), (PG8_LAS unsigned*)(lds + (bufoff) + ldsw + _i * 8192), 16, 0, 0); } while (0)
; #define PG8_LDA(dst, b, h) do { _Pragma("unroll") for (int m = 0; m < 4; ++m) _Pragma("unroll") for (int k = 0; k < 2; ++k) dst[m][k] = *(const PG8_LAS bf16x8*)(lds + PG8_SA(b, h) + aoff + m * 2048 + k * 1024); } while (0)
; #define PG8_MMA(ai, bj, At, Bt) do { __builtin_amdgcn_s_setprio(1); _Pragma("unroll") for (int m = 0; m < 4; ++m) _Pragma("unroll") for (int n = 0; n < 2; ++n) _Pragma("unroll") for (int k = 0; k < 2; ++k) \
;         acc[ai][bj][m][n] = __builtin_amdgcn_mfma_f32_16x16x32_bf16(Bt[n][k], At[m][k], acc[ai][bj][m][n], 0, 0, 0); __builtin_amdgcn_s_setprio(0); } while (0)
; #define PG8_WAIT_V(n) asm volatile("s_waitcnt vmcnt(" #n ")" ::: "memory")
; #define PG8_WAIT_L(n) asm volatile("s_waitcnt lgkmcnt(" #n ")" ::: "memory")
; #define PG8_BAR __builtin_amdgcn_s_barrier()
; #define PG8_SCHED __builtin_amdgcn_sched_barrier(0)
; template <class Epi, class Sched, bool ALIGN_EPI = false, bool SP2 = false>
; __device__ __forceinline__ void gemm_phase(PG8_LAS unsigned char* lds, const Gemm g, const Sched& S, const Epi& E) {
;     ...
;             PG8_LDA(At, 0, 1); PG8_STAGE(PG8_SB(0, 0), b2, voffB); PG8_STAGE(PG8_SB(0, 1), b2 + hstep, voffB); PG8_STAGE(PG8_SA(0, 0), a2, voffA);
;             PG8_WAIT_V(8); PG8_WAIT_L(0); PG8_BAR; PG8_MMA(1, 0, At, B0); PG8_MMA(1, 1, At, B1); PG8_BAR; PG8_SCHED;
	v_lshl_add_u64 v[198:199], s[24:25], 0, v[134:135]
	s_add_i32 m0, s35, 0x10000
	ds_read_b128 v[180:183], v166 offset:16384
	ds_read_b128 v[184:187], v166 offset:17408
	ds_read_b128 v[188:191], v166 offset:18432
	ds_read_b128 v[192:195], v166 offset:19456
	ds_read_b128 v[202:205], v166 offset:20480
	ds_read_b128 v[206:209], v166 offset:21504
	ds_read_b128 v[210:213], v166 offset:22528
	ds_read_b128 v[214:217], v166 offset:23552
	global_load_lds_dwordx4 v[198:199], off
	s_add_i32 m0, s35, 0x12000
	s_add_u32 s48, s24, 0x40000
	v_lshl_add_u64 v[218:219], s[24:25], 0, v[0:1]
	s_addc_u32 s49, s25, 0
	global_load_lds_dwordx4 v[218:219], off
	v_lshl_add_u64 v[220:221], s[48:49], 0, v[134:135]
	s_add_i32 m0, s35, 0x14000
	v_lshl_add_u64 v[222:223], s[26:27], 0, v[132:133]
	global_load_lds_dwordx4 v[220:221], off
	s_add_i32 m0, s35, 0x16000
	v_lshl_add_u64 v[220:221], s[48:49], 0, v[0:1]
	global_load_lds_dwordx4 v[220:221], off
	s_mov_b32 m0, s37
	v_lshl_add_u64 v[220:221], s[26:27], 0, v[136:137]
	global_load_lds_dwordx4 v[220:221], off
	s_mov_b32 m0, s38
	s_add_i32 s47, 0, 0x18000
	global_load_lds_dwordx4 v[222:223], off
	s_waitcnt vmcnt(8) lgkmcnt(0)
	s_barrier
	s_setprio 1
	v_mfma_f32_16x16x32_bf16 v[64:67], v[144:147], v[180:183], 0
	v_mfma_f32_16x16x32_bf16 v[56:59], v[152:155], v[180:183], 0
	v_mfma_f32_16x16x32_bf16 v[48:51], v[144:147], v[188:191], 0
	v_mfma_f32_16x16x32_bf16 v[40:43], v[152:155], v[188:191], 0
	v_mfma_f32_16x16x32_bf16 v[32:35], v[144:147], v[202:205], 0
	v_mfma_f32_16x16x32_bf16 v[24:27], v[152:155], v[202:205], 0
	v_mfma_f32_16x16x32_bf16 v[16:19], v[144:147], v[210:213], 0
	v_mfma_f32_16x16x32_bf16 v[8:11], v[152:155], v[210:213], 0
	v_mfma_f32_16x16x32_bf16 v[64:67], v[148:151], v[184:187], v[64:67]
	v_mfma_f32_16x16x32_bf16 v[56:59], v[156:159], v[184:187], v[56:59]
	v_mfma_f32_16x16x32_bf16 v[48:51], v[148:151], v[192:195], v[48:51]
	v_mfma_f32_16x16x32_bf16 v[40:43], v[156:159], v[192:195], v[40:43]
	v_mfma_f32_16x16x32_bf16 v[32:35], v[148:151], v[206:209], v[32:35]
	v_mfma_f32_16x16x32_bf16 v[24:27], v[156:159], v[206:209], v[24:27]
	v_mfma_f32_16x16x32_bf16 v[16:19], v[148:151], v[214:217], v[16:19]
	v_mfma_f32_16x16x32_bf16 v[8:11], v[156:159], v[214:217], v[8:11]
	s_setprio 0
	s_setprio 1
	v_mfma_f32_16x16x32_bf16 v[60:63], v[160:163], v[180:183], 0
	v_mfma_f32_16x16x32_bf16 v[52:55], v[172:175], v[180:183], 0
	v_mfma_f32_16x16x32_bf16 v[44:47], v[160:163], v[188:191], 0
	v_mfma_f32_16x16x32_bf16 v[36:39], v[172:175], v[188:191], 0
	v_mfma_f32_16x16x32_bf16 v[28:31], v[160:163], v[202:205], 0
	v_mfma_f32_16x16x32_bf16 v[20:23], v[172:175], v[202:205], 0
	v_mfma_f32_16x16x32_bf16 v[12:15], v[160:163], v[210:213], 0
	v_mfma_f32_16x16x32_bf16 v[4:7], v[172:175], v[210:213], 0
	v_mfma_f32_16x16x32_bf16 v[60:63], v[168:171], v[184:187], v[60:63]
	v_mfma_f32_16x16x32_bf16 v[52:55], v[176:179], v[184:187], v[52:55]
	v_mfma_f32_16x16x32_bf16 v[44:47], v[168:171], v[192:195], v[44:47]
	v_mfma_f32_16x16x32_bf16 v[36:39], v[176:179], v[192:195], v[36:39]
	v_mfma_f32_16x16x32_bf16 v[28:31], v[168:171], v[206:209], v[28:31]
	v_mfma_f32_16x16x32_bf16 v[20:23], v[176:179], v[206:209], v[20:23]
	v_mfma_f32_16x16x32_bf16 v[12:15], v[168:171], v[214:217], v[12:15]
	v_mfma_f32_16x16x32_bf16 v[4:7], v[176:179], v[214:217], v[4:7]
	s_setprio 0
	s_barrier
	s_branch .Lkmid_2
	.p2align	8

; #define PG8_STAGE(bufoff, gbase, voff) do { _Pragma("unroll") for (int _i = 0; _i < 2; ++_i) \
;         __builtin_amdgcn_global_load_lds((const unsigned*)((const char*)(gbase) + (voff)[_i]), (PG8_LAS unsigned*)(lds + (bufoff) + ldsw + _i * 8192), 16, 0, 0); } while (0)
; #define PG8_LDA(dst, b, h) do { _Pragma("unroll") for (int m = 0; m < 4; ++m) _Pragma("unroll") for (int k = 0; k < 2; ++k) dst[m][k] = *(const PG8_LAS bf16x8*)(lds + PG8_SA(b, h) + aoff + m * 2048 + k * 1024); } while (0)
; #define PG8_LDB(dst, b, h) do { _Pragma("unroll") for (int n = 0; n < 2; ++n) _Pragma("unroll") for (int k = 0; k < 2; ++k) dst[n][k] = *(const PG8_LAS bf16x8*)(lds + PG8_SB(b, h) + boff + n * 2048 + k * 1024); } while (0)
; #define PG8_MMA(ai, bj, At, Bt) do { __builtin_amdgcn_s_setprio(1); _Pragma("unroll") for (int m = 0; m < 4; ++m) _Pragma("unroll") for (int n = 0; n < 2; ++n) _Pragma("unroll") for (int k = 0; k < 2; ++k) \
;         acc[ai][bj][m][n] = __builtin_amdgcn_mfma_f32_16x16x32_bf16(Bt[n][k], At[m][k], acc[ai][bj][m][n], 0, 0, 0); __builtin_amdgcn_s_setprio(0); } while (0)
; #define PG8_WAIT_V(n) asm volatile("s_waitcnt vmcnt(" #n ")" ::: "memory")
; #define PG8_BAR __builtin_amdgcn_s_barrier()
; template <class Epi, class Sched, bool ALIGN_EPI = false, bool SP2 = false>
; __device__ __forceinline__ void gemm_phase(PG8_LAS unsigned char* lds, const Gemm g, const Sched& S, const Epi& E) {
;     ...
;         for (int t = 0; t < nt; t += 2) {
;             const bool last = (t == nt - 2);
;             const char* a1 = cA + (size_t)(t + 1) * kstep;
;             const char* a2 = last ? nA : cA + (size_t)(t + 2) * kstep; const char* b2 = last ? nB : cB + (size_t)(t + 2) * kstep;
;             const char* a3 = a2 + kstep; const char* b3 = b2 + kstep;
;             if (last && has_next) S.a_ready(nxt);
;             if constexpr (SP2) {
;             PG8_LDB(B0, 0, 0); PG8_LDB(B1, 0, 1); PG8_SCHED; PG8_LDA(At, 0, 0); PG8_STAGE(PG8_SA(1, 1), a1 + hstep, voffA);
;             PG8_WAIT_V(8); PG8_WAIT_L(0); PG8_BAR; PG8_MMA(0, 0, At, B0); PG8_MMA(0, 1, At, B1); PG8_BAR; PG8_SCHED;
;             PG8_LDA(At, 0, 1); PG8_STAGE(PG8_SB(0, 0), b2, voffB); PG8_STAGE(PG8_SB(0, 1), b2 + hstep, voffB); PG8_STAGE(PG8_SA(0, 0), a2, voffA);
;             PG8_WAIT_V(8); PG8_WAIT_L(0); PG8_BAR; PG8_MMA(1, 0, At, B0); PG8_MMA(1, 1, At, B1); PG8_BAR; PG8_SCHED;
.LBB0_479:
	s_add_u32 s44, s28, 0x100
	s_addc_u32 s45, s29, 0
	s_mov_b32 s53, -2
	s_add_u32 s8, s26, 0x100
	s_addc_u32 s9, s27, 0
	s_cmp_eq_u32 s53, 40
	s_cselect_b32 s31, s23, s9
	s_cselect_b32 s30, s22, s8
	s_cselect_b32 s29, s25, s45
	s_cselect_b32 s28, s24, s44
	ds_read_b128 v[68:71], v234
	ds_read_b128 v[80:83], v234 offset:1024
	ds_read_b128 v[92:95], v234 offset:2048
	ds_read_b128 v[100:103], v234 offset:3072
	ds_read_b128 v[112:115], v234 offset:16384
	ds_read_b128 v[120:123], v234 offset:17408
	ds_read_b128 v[132:135], v234 offset:18432
	ds_read_b128 v[144:147], v234 offset:19456
	v_lshl_add_u64 v[198:199], s[26:27], 0, v[204:205]
	s_add_i32 m0, s40, 0xc000
	ds_read_b128 v[156:159], v236
	ds_read_b128 v[168:171], v236 offset:1024
	ds_read_b128 v[172:175], v236 offset:2048
	ds_read_b128 v[176:179], v236 offset:3072
	ds_read_b128 v[180:183], v236 offset:4096
	ds_read_b128 v[184:187], v236 offset:5120
	ds_read_b128 v[188:191], v236 offset:6144
	ds_read_b128 v[208:211], v236 offset:7168
	global_load_lds_dwordx4 v[198:199], off
	s_add_i32 m0, s40, 0xe000
	v_lshl_add_u64 v[198:199], s[26:27], 0, v[206:207]
	global_load_lds_dwordx4 v[198:199], off
	s_waitcnt vmcnt(8) lgkmcnt(0)
	s_barrier
	s_setprio 1
	v_mfma_f32_16x16x32_bf16 v[164:167], v[68:71], v[156:159], 0
	v_mfma_f32_16x16x32_bf16 v[160:163], v[92:95], v[156:159], 0
	v_mfma_f32_16x16x32_bf16 v[140:143], v[68:71], v[172:175], 0
	v_mfma_f32_16x16x32_bf16 v[136:139], v[92:95], v[172:175], 0
	v_mfma_f32_16x16x32_bf16 v[116:119], v[68:71], v[180:183], 0
	v_mfma_f32_16x16x32_bf16 v[108:111], v[92:95], v[180:183], 0
	v_mfma_f32_16x16x32_bf16 v[88:91], v[68:71], v[188:191], 0
	v_mfma_f32_16x16x32_bf16 v[84:87], v[92:95], v[188:191], 0
	v_mfma_f32_16x16x32_bf16 v[164:167], v[80:83], v[168:171], v[164:167]
	v_mfma_f32_16x16x32_bf16 v[160:163], v[100:103], v[168:171], v[160:163]
	v_mfma_f32_16x16x32_bf16 v[140:143], v[80:83], v[176:179], v[140:143]
	v_mfma_f32_16x16x32_bf16 v[136:139], v[100:103], v[176:179], v[136:139]
	v_mfma_f32_16x16x32_bf16 v[116:119], v[80:83], v[184:187], v[116:119]
	v_mfma_f32_16x16x32_bf16 v[108:111], v[100:103], v[184:187], v[108:111]
	v_mfma_f32_16x16x32_bf16 v[88:91], v[80:83], v[208:211], v[88:91]
	v_mfma_f32_16x16x32_bf16 v[84:87], v[100:103], v[208:211], v[84:87]
	s_setprio 0
	s_setprio 1
	v_mfma_f32_16x16x32_bf16 v[152:155], v[112:115], v[156:159], 0
	v_mfma_f32_16x16x32_bf16 v[148:151], v[132:135], v[156:159], 0
	v_mfma_f32_16x16x32_bf16 v[128:131], v[112:115], v[172:175], 0
	v_mfma_f32_16x16x32_bf16 v[124:127], v[132:135], v[172:175], 0
	v_mfma_f32_16x16x32_bf16 v[104:107], v[112:115], v[180:183], 0
	v_mfma_f32_16x16x32_bf16 v[96:99], v[132:135], v[180:183], 0
	v_mfma_f32_16x16x32_bf16 v[76:79], v[112:115], v[188:191], 0
	v_mfma_f32_16x16x32_bf16 v[72:75], v[132:135], v[188:191], 0
	v_mfma_f32_16x16x32_bf16 v[152:155], v[120:123], v[168:171], v[152:155]
	v_mfma_f32_16x16x32_bf16 v[148:151], v[144:147], v[168:171], v[148:151]
	v_mfma_f32_16x16x32_bf16 v[128:131], v[120:123], v[176:179], v[128:131]
	v_mfma_f32_16x16x32_bf16 v[124:127], v[144:147], v[176:179], v[124:127]
	v_mfma_f32_16x16x32_bf16 v[104:107], v[120:123], v[184:187], v[104:107]
	v_mfma_f32_16x16x32_bf16 v[96:99], v[144:147], v[184:187], v[96:99]
	v_mfma_f32_16x16x32_bf16 v[76:79], v[120:123], v[208:211], v[76:79]
	v_mfma_f32_16x16x32_bf16 v[72:75], v[144:147], v[208:211], v[72:75]
	s_setprio 0
	s_barrier
	v_lshl_add_u64 v[198:199], s[28:29], 0, v[192:193]
	s_add_i32 m0, s39, 0x10000
	ds_read_b128 v[156:159], v236 offset:16384
	ds_read_b128 v[168:171], v236 offset:17408
	ds_read_b128 v[172:175], v236 offset:18432
	ds_read_b128 v[176:179], v236 offset:19456
	ds_read_b128 v[180:183], v236 offset:20480
	ds_read_b128 v[184:187], v236 offset:21504
	ds_read_b128 v[188:191], v236 offset:22528
	ds_read_b128 v[208:211], v236 offset:23552
	global_load_lds_dwordx4 v[198:199], off
	s_add_i32 m0, s39, 0x12000
	s_add_u32 s26, s28, 0xb0000
	v_lshl_add_u64 v[212:213], s[28:29], 0, v[202:203]
	s_addc_u32 s27, s29, 0
	global_load_lds_dwordx4 v[212:213], off
	v_lshl_add_u64 v[214:215], s[26:27], 0, v[192:193]
	s_add_i32 m0, s39, 0x14000
	v_lshl_add_u64 v[216:217], s[30:31], 0, v[194:195]
	global_load_lds_dwordx4 v[214:215], off
	s_add_i32 m0, s39, 0x16000
	v_lshl_add_u64 v[214:215], s[26:27], 0, v[202:203]
	global_load_lds_dwordx4 v[214:215], off
	s_mov_b32 m0, s40
	v_lshl_add_u64 v[214:215], s[30:31], 0, v[0:1]
	global_load_lds_dwordx4 v[214:215], off
	s_mov_b32 m0, s41
	s_add_i32 s54, 0, 0x18000
	global_load_lds_dwordx4 v[216:217], off
	s_waitcnt vmcnt(8) lgkmcnt(0)
	s_barrier
	s_setprio 1
	v_mfma_f32_16x16x32_bf16 v[64:67], v[68:71], v[156:159], 0
	v_mfma_f32_16x16x32_bf16 v[60:63], v[92:95], v[156:159], 0
	v_mfma_f32_16x16x32_bf16 v[48:51], v[68:71], v[172:175], 0
	v_mfma_f32_16x16x32_bf16 v[44:47], v[92:95], v[172:175], 0
	v_mfma_f32_16x16x32_bf16 v[32:35], v[68:71], v[180:183], 0
	v_mfma_f32_16x16x32_bf16 v[28:31], v[92:95], v[180:183], 0
	v_mfma_f32_16x16x32_bf16 v[16:19], v[68:71], v[188:191], 0
	v_mfma_f32_16x16x32_bf16 v[12:15], v[92:95], v[188:191], 0
	v_mfma_f32_16x16x32_bf16 v[64:67], v[80:83], v[168:171], v[64:67]
	v_mfma_f32_16x16x32_bf16 v[60:63], v[100:103], v[168:171], v[60:63]
	v_mfma_f32_16x16x32_bf16 v[48:51], v[80:83], v[176:179], v[48:51]
	v_mfma_f32_16x16x32_bf16 v[44:47], v[100:103], v[176:179], v[44:47]
	v_mfma_f32_16x16x32_bf16 v[32:35], v[80:83], v[184:187], v[32:35]
	v_mfma_f32_16x16x32_bf16 v[28:31], v[100:103], v[184:187], v[28:31]
	v_mfma_f32_16x16x32_bf16 v[16:19], v[80:83], v[208:211], v[16:19]
	v_mfma_f32_16x16x32_bf16 v[12:15], v[100:103], v[208:211], v[12:15]
	s_setprio 0
	s_setprio 1
	v_mfma_f32_16x16x32_bf16 v[56:59], v[112:115], v[156:159], 0
	v_mfma_f32_16x16x32_bf16 v[52:55], v[132:135], v[156:159], 0
	v_mfma_f32_16x16x32_bf16 v[40:43], v[112:115], v[172:175], 0
	v_mfma_f32_16x16x32_bf16 v[36:39], v[132:135], v[172:175], 0
	v_mfma_f32_16x16x32_bf16 v[24:27], v[112:115], v[180:183], 0
	v_mfma_f32_16x16x32_bf16 v[20:23], v[132:135], v[180:183], 0
	v_mfma_f32_16x16x32_bf16 v[8:11], v[112:115], v[188:191], 0
	v_mfma_f32_16x16x32_bf16 v[4:7], v[132:135], v[188:191], 0
	v_mfma_f32_16x16x32_bf16 v[56:59], v[120:123], v[168:171], v[56:59]
	v_mfma_f32_16x16x32_bf16 v[52:55], v[144:147], v[168:171], v[52:55]
	v_mfma_f32_16x16x32_bf16 v[40:43], v[120:123], v[176:179], v[40:43]
	v_mfma_f32_16x16x32_bf16 v[36:39], v[144:147], v[176:179], v[36:39]
	v_mfma_f32_16x16x32_bf16 v[24:27], v[120:123], v[184:187], v[24:27]
	v_mfma_f32_16x16x32_bf16 v[20:23], v[144:147], v[184:187], v[20:23]
	v_mfma_f32_16x16x32_bf16 v[8:11], v[120:123], v[208:211], v[8:11]
	v_mfma_f32_16x16x32_bf16 v[4:7], v[144:147], v[208:211], v[4:7]
	s_setprio 0
	s_barrier
	s_branch .Lkmid_3
	.p2align	8
